# free start stagger extended to the in-projection GEMM: the 32 workgroups with a spare tile slot (bx>=224) start ~half a tile late (power/burst de-synchronisation), on top of the best version
# speedup vs baseline: 1.0018x; 1.0018x over previous
.LBB0_295:
	s_or_b64 exec, exec, s[0:1]
	v_mov_b32_e32 v10, v1
	s_cmpk_lt_i32 s96, 0xde0
	s_waitcnt lgkmcnt(0)
	s_barrier
	s_cselect_b64 s[0:1], -1, 0
	s_cmpk_lt_i32 s96, 0xe0
	s_cbranch_scc1 .Lp2_nostagger
	s_sleep 127
	s_sleep 127
	s_sleep 127
	s_sleep 127
.Lp2_nostagger:
	s_cmpk_gt_i32 s96, 0xddf
	v_readfirstlane_b32 s8, v10
	s_cbranch_scc1 .LBB0_297
	s_ashr_i32 s2, s96, 31
	s_lshr_b32 s2, s2, 29
	s_add_i32 s2, s96, s2
	s_ashr_i32 s3, s2, 3
	s_and_b32 s2, s2, -8
	s_sub_i32 s2, s96, s2
	s_cmp_lt_i32 s2, 0
	s_movk_i32 s4, 0x1bd
	s_cselect_b32 s4, s4, 0x1bc
	s_mul_i32 s2, s2, s4
	s_add_i32 s2, s2, s3
	s_mul_hi_i32 s3, s2, 0xdd67c8a7
	s_add_i32 s3, s3, s2
	s_lshr_b32 s4, s3, 31
	s_ashr_i32 s3, s3, 8
	s_add_i32 s3, s3, s4
	s_lshl_b32 s4, s3, 3
	s_mulk_i32 s3, 0x128
	s_sub_i32 s2, s2, s3
	s_sext_i32_i16 s3, s2
	s_bfe_u32 s3, s3, 0x3001c
	s_add_i32 s3, s2, s3
	s_sext_i32_i16 s5, s3
	s_and_b32 s3, s3, 0xfff8
	s_sub_i32 s2, s2, s3
	s_sext_i32_i16 s2, s2
	s_add_i32 s26, s4, s2
	s_ashr_i32 s2, s5, 3
